# v112 + DSA item: waves 4-7 at s_setprio 1 from the index-score phase to the end of the sparse attention
# speedup vs baseline: 1.0031x; 1.0031x over previous
; #define LAS __attribute__((address_space(3)))
; __device__ __forceinline__ float bf2f(u16 b) { return __uint_as_float(((unsigned)b) << 16); }
;     const int tid = opq(threadIdx.x), wid = __builtin_amdgcn_readfirstlane(tid >> 6), lane = tid & 63;
;     const int t0 = rq * 8, nmax = t0 + 8, ntile32 = (nmax + 31) >> 5;
;     const u16* prow = p.proj + (size_t)bl * SEQ * NP;
;     LAS float* sc = (LAS float*)lds;
;     { const int c32 = lane & 31, hi = lane >> 5;
;       bf16x8 qa[4];
;       { const u16* qp = prow + (size_t)(t0 + (c32 >> 2)) * NP + C_QI + (c32 & 3) * 64 + 8 * hi;
; #pragma unroll
;         for (int ks = 0; ks < 4; ++ks) qa[ks] = *(const bf16x8*)(qp + ks * 16); }
;       float wv[16];
; #pragma unroll
;       for (int r = 0; r < 16; ++r) wv[r] = 0.5f * bf2f(prow[(size_t)(t0 + 2 * (r >> 2) + hi) * NP + C_WI + (r & 3)]);
; #pragma unroll
;       for (int r = 0; r < 16; ++r) wv[r] *= 0.125f;
;       auto ldb = [&](bf16x8 (&kk)[4][4], int i0) {
; #pragma unroll
;           for (int j = 0; j < 4; ++j) { int T = wid + 8 * (i0 + j); T = T < ntile32 ? T : ntile32 - 1; const u16* kp = p.kiP + (((size_t)bl * 128 + T) * 256 + lane) * 8;
; #pragma unroll
;               for (int ks = 0; ks < 4; ++ks) kk[j][ks] = *(const bf16x8*)(kp + ks * 512); } };
;       auto comp = [&](const bf16x8 (&kk)[4][4], int i0) {
; #pragma unroll
;           for (int j = 0; j < 4; ++j) {
;               const int T = wid + 8 * (i0 + j);
;               if (T < ntile32) {
;                   const int key = T * 32 + c32;
;                   f32x16 a;
; #pragma unroll
;                   for (int r = 0; r < 16; ++r) a[r] = 0.f;
; #pragma unroll
;                   for (int ks = 0; ks < 4; ++ks) a = __builtin_amdgcn_mfma_f32_32x32x16_bf16(qa[ks], kk[j][ks], a, 0, 0, 0);
; #pragma unroll
;                   for (int g4 = 0; g4 < 4; ++g4) { float s = 0.f;
; #pragma unroll
;                       for (int hh = 0; hh < 4; ++hh) s = fmaf(wv[4 * g4 + hh], fmaxf(a[4 * g4 + hh], 0.f), s);
;                       sc[(2 * g4 + hi) * 4096 + key] = s; }
;               }
;           } };
;       if (sm & 1) {
;           const int nT = (ntile32 - wid + 7) >> 3;
;           bf16x8 ka[4][4], kc[4][4];
;           ldb(ka, 0);
;           for (int i0 = 0; i0 < nT; i0 += 8) { ldb(kc, i0 + 4); comp(ka, i0); ldb(ka, i0 + 8); comp(kc, i0 + 4); }
.LBB0_178:
	s_and_b64 vcc, exec, s[38:39]
	s_cbranch_vccz .LBB0_970
	s_lshl_b32 s0, s58, 1
	s_and_b32 s37, s58, 3
	s_and_b32 s0, s0, 0x1ff8
	v_mov_b32_e32 v174, v198
	s_sub_i32 s30, 0x11f8, s0
	s_sub_i32 s0, 0x1218, s0
	s_mul_i32 s1, s37, 0x5800000
	s_add_u32 s54, s14, s1
	v_readfirstlane_b32 s59, v174
	s_addc_u32 s55, s15, 0
	s_ashr_i32 s64, s59, 6
	s_lshr_b32 s0, s0, 5
	s_sub_i32 s1, s0, s64
	s_add_i32 s1, s1, 7
	s_ashr_i32 s1, s1, 3
	s_cmp_lt_i32 s1, 1
	v_and_b32_e32 v163, 63, v174
	s_cbranch_scc1 .LBB0_198
	s_cmp_lt_u32 s59, 0x100
	s_cbranch_scc1 .Ldsa_prio_skip
	s_setprio 1
.Ldsa_prio_skip:
	v_lshrrev_b32_e32 v14, 5, v163
	v_or_b32_e32 v0, s30, v14
	v_mul_i32_i24_e32 v0, 0x5800, v0
	v_lshl_add_u64 v[2:3], s[54:55], 0, v[0:1]
	v_add_co_u32_e32 v4, vcc, 0x1000, v2
	s_mov_b32 s20, 0xc000
	s_nop 0
	v_addc_co_u32_e32 v5, vcc, 0, v3, vcc
	v_bfe_u32 v0, v174, 2, 3
	v_add_co_u32_e32 v6, vcc, s20, v2
	v_or_b32_e32 v0, s30, v0
	s_nop 0
	v_addc_co_u32_e32 v7, vcc, 0, v3, vcc
	s_mov_b32 s20, 0x17000
	v_mul_i32_i24_e32 v0, 0x2c00, v0
	v_add_co_u32_e32 v8, vcc, s20, v2
	v_lshl_add_u64 v[10:11], v[0:1], 1, s[54:55]
	v_lshlrev_b32_e32 v0, 7, v163
	v_addc_co_u32_e32 v9, vcc, 0, v3, vcc
	s_mov_b32 s20, 0x22000
	v_and_b32_e32 v0, 0x180, v0
	v_add_co_u32_e32 v2, vcc, s20, v2
	v_lshl_add_u64 v[10:11], v[10:11], 0, v[0:1]
	v_lshlrev_b32_e32 v0, 4, v14
	v_addc_co_u32_e32 v3, vcc, 0, v3, vcc
	v_lshl_add_u64 v[10:11], v[10:11], 0, v[0:1]
	s_mov_b64 s[22:23], 0x1100
	s_movk_i32 s21, 0x1000
	s_add_i32 s20, s0, -1
	v_lshl_add_u64 v[12:13], v[10:11], 0, s[22:23]
	v_add_co_u32_e32 v10, vcc, s21, v10
	s_add_i32 s21, s64, 24
	s_min_i32 s22, s21, s20
	s_ashr_i32 s23, s22, 31
	s_lshl_b32 s24, s37, 15
	s_lshl_b64 s[22:23], s[22:23], 8
	s_add_u32 s21, s22, s24
	global_load_dwordx2 v[4:5], v[4:5], off offset:896
	s_nop 0
	global_load_dwordx2 v[6:7], v[6:7], off offset:896
	s_nop 0
	global_load_dwordx2 v[8:9], v[8:9], off offset:896
	s_nop 0
	global_load_dwordx2 v[2:3], v[2:3], off offset:896
	s_nop 0
	global_load_dwordx4 v[18:21], v[12:13], off offset:64
	global_load_dwordx4 v[22:25], v[12:13], off offset:32
	v_addc_co_u32_e32 v11, vcc, 0, v11, vcc
	global_load_dwordx4 v[26:29], v[12:13], off offset:96
	global_load_dwordx4 v[30:33], v[10:11], off offset:256
	s_addc_u32 s22, s23, 0
	v_or_b32_e32 v10, s21, v163
	s_add_i32 s21, s64, 16
	v_mov_b32_e32 v11, s22
	s_min_i32 s22, s21, s20
	v_readlane_b32 s40, v251, 1
	s_ashr_i32 s23, s22, 31
	v_readlane_b32 s41, v251, 2
	s_lshl_b64 s[22:23], s[22:23], 8
	s_add_u32 s21, s22, s24
	v_lshl_add_u64 v[10:11], v[10:11], 4, s[40:41]
	global_load_dwordx4 v[34:37], v[10:11], off offset:3072
	global_load_dwordx4 v[38:41], v[10:11], off offset:2048
	global_load_dwordx4 v[42:45], v[10:11], off offset:1024
	global_load_dwordx4 v[46:49], v[10:11], off
	s_addc_u32 s22, s23, 0
	v_or_b32_e32 v10, s21, v163
	s_add_i32 s21, s64, 8
	v_mov_b32_e32 v11, s22
	s_min_i32 s22, s21, s20
	s_ashr_i32 s23, s22, 31
	s_lshl_b64 s[22:23], s[22:23], 8
	s_add_u32 s21, s22, s24
	v_lshl_add_u64 v[10:11], v[10:11], 4, s[40:41]
	s_addc_u32 s22, s23, 0
	global_load_dwordx4 v[50:53], v[10:11], off offset:3072
	global_load_dwordx4 v[54:57], v[10:11], off offset:2048
	global_load_dwordx4 v[58:61], v[10:11], off offset:1024
	global_load_dwordx4 v[62:65], v[10:11], off
	v_mov_b32_e32 v11, s22
	s_min_i32 s22, s64, s20
	s_ashr_i32 s23, s22, 31
	s_lshl_b64 s[22:23], s[22:23], 8
	v_or_b32_e32 v10, s21, v163
	s_add_u32 s21, s22, s24
	v_lshl_add_u64 v[10:11], v[10:11], 4, s[40:41]
	s_addc_u32 s22, s23, 0
	global_load_dwordx4 v[82:85], v[10:11], off offset:3072
	global_load_dwordx4 v[86:89], v[10:11], off offset:2048
	global_load_dwordx4 v[90:93], v[10:11], off offset:1024
	global_load_dwordx4 v[94:97], v[10:11], off
	v_or_b32_e32 v10, s21, v163
	v_mov_b32_e32 v11, s22
	v_lshl_add_u64 v[10:11], v[10:11], 4, s[40:41]
	global_load_dwordx4 v[114:117], v[10:11], off offset:3072
	global_load_dwordx4 v[118:121], v[10:11], off offset:2048
	global_load_dwordx4 v[122:125], v[10:11], off offset:1024
	global_load_dwordx4 v[126:129], v[10:11], off
	s_lshl_b32 s23, s64, 7
	s_mov_b32 s21, 0
	s_add_i32 s22, s64, 0x58
	v_readlane_b32 s42, v251, 3
	v_readlane_b32 s43, v251, 4
	v_readlane_b32 s44, v251, 5
	v_readlane_b32 s45, v251, 6
	v_readlane_b32 s46, v251, 7
	v_readlane_b32 s47, v251, 8
	s_waitcnt vmcnt(0)
	v_lshlrev_b32_e32 v0, 16, v4
	v_mul_f32_e32 v0, 0.5, v0
	v_mul_f32_e32 v175, 0x3e000000, v0
	s_waitcnt vmcnt(20)
	v_lshlrev_b32_e32 v16, 16, v2
	v_and_b32_e32 v2, 0xffff0000, v2
	v_or_b32_e32 v0, s24, v163
	v_mul_f32_e32 v2, 0.5, v2
	v_lshlrev_b32_e32 v0, 4, v0
	v_and_b32_e32 v4, 0xffff0000, v4
	v_lshlrev_b32_e32 v10, 16, v5
	v_and_b32_e32 v5, 0xffff0000, v5
	v_lshlrev_b32_e32 v11, 16, v6
	v_and_b32_e32 v6, 0xffff0000, v6
	v_lshlrev_b32_e32 v12, 16, v7
	v_and_b32_e32 v7, 0xffff0000, v7
	v_lshlrev_b32_e32 v13, 16, v8
	v_and_b32_e32 v8, 0xffff0000, v8
	v_lshlrev_b32_e32 v15, 16, v9
	v_and_b32_e32 v9, 0xffff0000, v9
	v_lshlrev_b32_e32 v17, 16, v3
	v_and_b32_e32 v3, 0xffff0000, v3
	v_mul_f32_e32 v189, 0x3e000000, v2
	v_and_b32_e32 v2, 31, v174
	v_lshl_add_u64 v[172:173], s[40:41], 0, v[0:1]
	v_lshl_add_u32 v0, v14, 14, s23
	v_mul_f32_e32 v4, 0.5, v4
	v_mul_f32_e32 v10, 0.5, v10
	v_mul_f32_e32 v5, 0.5, v5
	v_mul_f32_e32 v11, 0.5, v11
	v_mul_f32_e32 v6, 0.5, v6
	v_mul_f32_e32 v12, 0.5, v12
	v_mul_f32_e32 v7, 0.5, v7
	v_mul_f32_e32 v13, 0.5, v13
	v_mul_f32_e32 v8, 0.5, v8
	v_mul_f32_e32 v15, 0.5, v15
	v_mul_f32_e32 v9, 0.5, v9
	v_mul_f32_e32 v16, 0.5, v16
	v_mul_f32_e32 v17, 0.5, v17
	v_mul_f32_e32 v3, 0.5, v3
	v_lshl_or_b32 v0, v2, 2, v0
	v_mul_f32_e32 v176, 0x3e000000, v4
	v_mul_f32_e32 v177, 0x3e000000, v10
	v_mul_f32_e32 v178, 0x3e000000, v5
	v_mul_f32_e32 v179, 0x3e000000, v11
	v_mul_f32_e32 v181, 0x3e000000, v6
	v_mul_f32_e32 v182, 0x3e000000, v12
	v_mul_f32_e32 v183, 0x3e000000, v7
	v_mul_f32_e32 v184, 0x3e000000, v13
	v_mul_f32_e32 v185, 0x3e000000, v8
	v_mul_f32_e32 v186, 0x3e000000, v15
	v_mul_f32_e32 v187, 0x3e000000, v9
	v_mul_f32_e32 v188, 0x3e000000, v16
	v_mul_f32_e32 v190, 0x3e000000, v17
	v_mul_f32_e32 v191, 0x3e000000, v3
	v_add_u32_e32 v0, 0, v0
	s_branch .LBB0_182
